# MLA tile loop: online-softmax reference folded into the QK MFMA accumulator init (C = -m quad), 8 v_sub per head-half removed from the common path; reference starts at 0 and rescale works on relative
# speedup vs baseline: 1.0067x; 1.0067x over previous
; DEVI int opaque_tid(int wv) { int t; asm volatile("v_mbcnt_lo_u32_b32 %0, -1, 0\n\tv_mbcnt_hi_u32_b32 %0, -1, %0" : "=v"(t)); return wv * 64 + t; }
; DEVI void mla_item(const Ctx& cx, int b, int h, int qt, unsigned char* lds, int wv) {
;   const int tid = opaque_tid(wv), lane = tid & 63, wave = tid >> 6, idx = lane & 15, quad = lane >> 4;
;   const int t0 = qt * 256;
;   const int lc = tid & 7, lr = tid >> 3;
;   const int lc2 = tid & 3, lr2 = (tid >> 2) & 63;
;   int tq[2];
;   bf16x8 q[2][3];
;   f32x4 o[2][4]; float mr[2], lrn[2];
; #pragma unroll
;   for (int c = 0; c < 2; ++c) {
;     tq[c] = t0 + wave * 32 + c * 16 + idx;
; #pragma unroll
;     for (int ks = 0; ks < 3; ++ks) q[c][ks] = *(const bf16x8*)(cx.qm + ((size_t)(b * S + tq[c])) * 512 + h * 96 + ks * 32 + quad * 8);
;     mr[c] = -1e29f; lrn[c] = 0.f;
; #pragma unroll
;     for (int d = 0; d < 4; ++d) o[c][d] = (f32x4){0.f, 0.f, 0.f, 0.f};
;   }
;   const int wave_tmax = t0 + wave * 32 + 31;
;   const int ntiles = 4 * qt + 4;
;   u32x4 kr, vr, pr;
;   auto gload = [&](int m) {
;     kr = *(const u32x4*)(cx.kn + ((size_t)(b * S + m * 64 + lr)) * 320 + h * 64 + lc * 8);
;     vr = *(const u32x4*)(cx.mlavT + ((size_t)((b * 5 + h) * 64 + lr)) * S + m * 64 + lc * 8);
;     if (tid < 256) pr = *(const u32x4*)(cx.proj + ((size_t)(b * S + m * 64 + lr2)) * PS + C_KPE + lc2 * 8);
;   };
;   auto lwrite = [&](int bi) {
;     *(u32x4*)(lds + ATT_K0 + bi * ATT_KSZ + lr * KROW_MLA + lc * 16) = kr;
;     *(u32x4*)(lds + ATT_V0 + bi * ATT_VSZ + lr * LDS_ROW + lc * 16) = vr;
;     if (tid < 256) *(u32x4*)(lds + ATT_K0 + bi * ATT_KSZ + lr2 * KROW_MLA + 128 + lc2 * 16) = pr;
;   };
;   gload(0); lwrite(0);
;   __syncthreads();
;   int bi = 0;
.LBB0_1356:
	s_or_b64 exec, exec, s[6:7]
	s_movk_i32 s6, 0xd0
	v_mul_lo_u32 v112, v42, s6
	v_add3_u32 v32, 0, v112, v90
	v_lshlrev_b32_e32 v48, 6, v42
	v_sub_u32_e32 v113, v32, v48
	s_waitcnt vmcnt(1)
	ds_write_b128 v32, v[24:27]
	s_waitcnt vmcnt(0)
	ds_write_b128 v113, v[28:31] offset:26624
	s_and_saveexec_b64 s[6:7], vcc
	s_xor_b64 s[6:7], exec, s[6:7]
	v_lshlrev_b32_e32 v114, 4, v47
	s_or_saveexec_b64 s[6:7], s[6:7]
	v_mul_u32_u24_e32 v116, 0xd0, v45
	s_xor_b64 exec, exec, s[6:7]
	v_add3_u32 v32, 0, v116, v40
	v_mov_b32_e32 v114, v40
	ds_write_b128 v32, v[34:37] offset:128
	s_or_b64 exec, exec, s[6:7]
	v_lshlrev_b32_e32 v32, 3, v44
	v_lshl_add_u32 v47, v44, 4, 0
	s_movk_i32 s6, 0xd0
	v_mad_u32_u24 v118, v41, s6, v47
	v_sub_u32_e32 v32, v47, v32
	s_movk_i32 s6, 0x90
	v_mad_u32_u24 v119, v41, s6, v32
	s_lshl_b64 s[6:7], s[4:5], 1
	v_readlane_b32 s4, v253, 28
	v_lshlrev_b32_e32 v46, 3, v46
	v_readlane_b32 s5, v253, 29
	s_add_u32 s4, s4, s6
	s_addc_u32 s5, s5, s7
	v_lshlrev_b32_e32 v32, 1, v46
	v_readlane_b32 s20, v252, 40
	v_lshl_add_u64 v[94:95], s[4:5], 0, v[32:33]
	v_mov_b32_e32 v41, v33
	v_readlane_b32 s22, v252, 42
	v_readlane_b32 s23, v252, 43
	v_mov_b32_e32 v91, v33
	v_readlane_b32 s4, v254, 46
	v_lshlrev_b32_e32 v43, 2, v43
	v_lshl_add_u64 v[96:97], s[22:23], 0, v[40:41]
	v_lshl_add_u64 v[38:39], v[38:39], 0, v[90:91]
	v_readlane_b32 s5, v254, 47
	s_add_i32 s8, s8, 64
	v_mov_b32_e32 v40, v33
	v_lshlrev_b32_e32 v115, 2, v44
	v_bitop3_b32 v110, v43, s58, v237 bitop3:0x6c
	v_lshl_add_u64 v[98:99], s[4:5], 0, v[38:39]
	v_add_u32_e32 v91, s8, v45
	v_add_u32_e32 v122, s8, v42
	v_mov_b32_e32 v131, v130
	v_mov_b32_e32 v32, v33
	v_mov_b32_e32 v38, v33
	v_mov_b32_e32 v39, v33
	v_mov_b64_e32 v[44:45], v[40:41]
	v_mov_b64_e32 v[48:49], v[40:41]
	v_mov_b64_e32 v[52:53], v[40:41]
	v_mov_b64_e32 v[56:57], v[40:41]
	v_mov_b64_e32 v[60:61], v[40:41]
	v_mov_b64_e32 v[64:65], v[40:41]
	v_mov_b64_e32 v[68:69], v[40:41]
	v_or_b32_e32 v117, 31, v108
	v_add_u32_e32 v120, 14, v109
	v_add_u32_e32 v121, 13, v109
	s_mov_b32 s16, 1
	s_mov_b32 s17, 0
	v_mov_b64_e32 v[42:43], v[38:39]
	v_mov_b64_e32 v[46:47], v[38:39]
	v_mov_b64_e32 v[50:51], v[38:39]
	v_mov_b64_e32 v[54:55], v[38:39]
	v_mov_b64_e32 v[58:59], v[38:39]
	v_mov_b64_e32 v[62:63], v[38:39]
	v_mov_b64_e32 v[66:67], v[38:39]
	s_mov_b32 s18, 0
	v_mov_b64_e32 v[92:93], v[32:33]
	v_mov_b32_e32 v100, 0
	v_mov_b32_e32 v101, 0
	v_mov_b32_e32 v186, 0
	v_mov_b32_e32 v187, 0
	v_mov_b32_e32 v188, 0
	v_mov_b32_e32 v189, 0
	v_mov_b32_e32 v190, 0
	v_mov_b32_e32 v191, 0
	v_mov_b32_e32 v192, 0
	v_mov_b32_e32 v193, 0
	s_waitcnt lgkmcnt(0)
	s_barrier
	v_readlane_b32 s21, v252, 41
	s_branch .LBB0_1363

; template <int NC, int KS>
; DEVI void qk_half(const unsigned char* Kl, int krow, const bf16x8 (&q)[NC][KS], f32x4 (&s)[NC][2], int idx, int quad) {
; #pragma unroll
;   for (int u = 0; u < 2; ++u) {
; #pragma unroll
;     for (int c = 0; c < NC; ++c) s[c][u] = (f32x4){0.f, 0.f, 0.f, 0.f};
; #pragma unroll
;     for (int ks = 0; ks < KS; ++ks) {
;       bf16x8 kf = *(const bf16x8*)(Kl + (u * 16 + idx) * krow + ks * 64 + quad * 16);
; #pragma unroll
;       for (int c = 0; c < NC; ++c) s[c][u] = mfma16(kf, q[c][ks], s[c][u]);
;     }
;   }
; }
; template <int NC>
; DEVI void pv_half(const unsigned char* Vl, int vrow, const bf16x8 (&pb)[NC], f32x4 (&o)[NC][4], int idx, int quad) {
; #pragma unroll
;   for (int dvt = 0; dvt < 4; ++dvt) {
;     const unsigned char* p = Vl + (dvt * 16 + idx) * vrow + quad * 8;
;     u32x2 lo = *(const u32x2*)p, hi = *(const u32x2*)(p + 32);
;     bf16x8 vf = as_bf8((u32x4){lo.x, lo.y, hi.x, hi.y});
; #pragma unroll
;     for (int c = 0; c < NC; ++c) o[c][dvt] = mfma16(vf, pb[c], o[c][dvt]);
;   }
; }
; DEVI bf16x8 pack_p(const f32x4& a, const f32x4& b) { return as_bf8((u32x4){pk2(a[0], a[1]), pk2(a[2], a[3]), pk2(b[0], b[1]), pk2(b[2], b[3])}); }
; template <int NC, int KS, class MaskF>
; DEVI void attn_tile(const unsigned char* Kl, int krow, const unsigned char* Vl, const bf16x8 (&q)[NC][KS], f32x4 (&o)[NC][4],
;                     float (&mr)[NC], float (&lr)[NC], int idx, int quad, int mask_mode, bool lane_ok, const MaskF& mf) {
; #pragma unroll
;   for (int hf = 0; hf < 2; ++hf) {
;     f32x4 s[NC][2];
;     qk_half<NC, KS>(Kl + hf * 32 * krow, krow, q, s, idx, quad);
;     bf16x8 pb[NC];
; #pragma unroll
;     for (int c = 0; c < NC; ++c) {
;       if (mask_mode == 2) {
; #pragma unroll
;         for (int u = 0; u < 2; ++u)
; #pragma unroll
;           for (int j = 0; j < 4; ++j) s[c][u][j] = mf(c, hf * 32 + u * 16 + quad * 4 + j) ? s[c][u][j] : -1e30f;
;       } else if (mask_mode == 1) {
; #pragma unroll
;         for (int u = 0; u < 2; ++u)
; #pragma unroll
;           for (int j = 0; j < 4; ++j) s[c][u][j] = lane_ok ? s[c][u][j] : -1e30f;
;       }
;       float ps = 0.f;
;       f32x4 p0, p1;
; #pragma unroll
;       for (int j = 0; j < 4; ++j) { p0[j] = fexp2(s[c][0][j] - mr[c]); p1[j] = fexp2(s[c][1][j] - mr[c]); ps += p0[j] + p1[j]; }
;       if (__builtin_amdgcn_ballot_w64(!(ps <= 2048.f)) != 0ull) {
.LBB0_1369:
	s_mul_i32 s4, s18, 0x3400
	v_add_u32_e32 v123, s4, v118
	ds_read_b128 v[70:73], v123
	ds_read_b128 v[78:81], v123 offset:64
	ds_read_b128 v[82:85], v123 offset:128
	ds_read_b128 v[102:105], v123 offset:3392
	s_add_i32 s4, s17, 63
	v_add_u32_e32 v124, s17, v115
	v_cmp_gt_i32_e64 s[4:5], s4, v108
	v_add_u32_e32 v126, 2, v124
	v_add_u32_e32 v125, 3, v124
	s_waitcnt lgkmcnt(3)
	v_mfma_f32_16x16x32_bf16 v[74:77], v[70:73], v[0:3], v[186:189]
	v_mfma_f32_16x16x32_bf16 v[70:73], v[70:73], v[12:15], v[190:193]
	s_waitcnt lgkmcnt(2)
	v_mfma_f32_16x16x32_bf16 v[74:77], v[78:81], v[4:7], v[74:77]
	v_mfma_f32_16x16x32_bf16 v[70:73], v[78:81], v[16:19], v[70:73]
	s_waitcnt lgkmcnt(1)
	v_mfma_f32_16x16x32_bf16 v[78:81], v[82:85], v[8:11], v[74:77]
	s_nop 4
	ds_read_b128 v[74:77], v123 offset:3328
	v_mfma_f32_16x16x32_bf16 v[70:73], v[82:85], v[20:23], v[70:73]
	s_waitcnt lgkmcnt(0)
	v_mfma_f32_16x16x32_bf16 v[82:85], v[74:77], v[0:3], v[186:189]
	v_mfma_f32_16x16x32_bf16 v[74:77], v[74:77], v[12:15], v[190:193]
	v_mfma_f32_16x16x32_bf16 v[82:85], v[102:105], v[4:7], v[82:85]
	v_mfma_f32_16x16x32_bf16 v[74:77], v[102:105], v[16:19], v[74:77]
	ds_read_b128 v[102:105], v123 offset:3456
	s_waitcnt lgkmcnt(0)
	v_mfma_f32_16x16x32_bf16 v[82:85], v[102:105], v[8:11], v[82:85]
	v_mfma_f32_16x16x32_bf16 v[74:77], v[102:105], v[20:23], v[74:77]
	s_and_saveexec_b64 s[12:13], s[4:5]
	s_cbranch_execz .LBB0_1371
	v_cmp_le_i32_e32 vcc, v124, v109
	v_add_u32_e32 v32, 16, v124
	s_nop 0
	v_cndmask_b32_e32 v78, v238, v78, vcc
	v_cmp_lt_i32_e32 vcc, v124, v109
	s_nop 1
	v_cndmask_b32_e32 v79, v238, v79, vcc
	v_cmp_le_i32_e32 vcc, v126, v109
	s_nop 1
	v_cndmask_b32_e32 v80, v238, v80, vcc
	v_cmp_le_i32_e32 vcc, v125, v109
	s_nop 1
	v_cndmask_b32_e32 v81, v238, v81, vcc
	v_cmp_le_i32_e32 vcc, v32, v109
	v_add_u32_e32 v32, 17, v124
	s_nop 0
	v_cndmask_b32_e32 v82, v238, v82, vcc
	v_cmp_le_i32_e32 vcc, v32, v109
	v_add_u32_e32 v32, 18, v124
	s_nop 0
	v_cndmask_b32_e32 v83, v238, v83, vcc
	v_cmp_le_i32_e32 vcc, v32, v109
	v_add_u32_e32 v32, 19, v124
	s_nop 0
	v_cndmask_b32_e32 v84, v238, v84, vcc
	v_cmp_le_i32_e32 vcc, v32, v109
	s_nop 1
	v_cndmask_b32_e32 v85, v238, v85, vcc
.LBB0_1371:
	s_or_b64 exec, exec, s[12:13]
	v_exp_f32_e32 v127, v78
	s_nop 1
	s_nop 0
	v_exp_f32_e32 v128, v82
	v_exp_f32_e32 v32, v79
	v_exp_f32_e32 v102, v83
	v_add_f32_e32 v103, v128, v127
	v_pk_add_f32 v[104:105], v[102:103], v[32:33]
	v_exp_f32_e32 v129, v80
	v_pk_add_f32 v[104:105], v[104:105], v[104:105] op_sel_hi:[0,1]
	v_exp_f32_e32 v131, v84
	v_exp_f32_e32 v104, v81
	v_exp_f32_e32 v106, v85
	v_add_f32_e32 v107, v131, v129
	v_pk_add_f32 v[132:133], v[106:107], v[104:105]
	s_nop 0
	v_add_f32_e32 v103, v132, v133
	v_cmp_nge_f32_e32 vcc, s94, v103
	s_cbranch_vccz .LBB0_1373
	v_max_f32_e32 v32, v79, v79
	v_max_f32_e32 v102, v78, v78
	v_max_f32_e32 v32, v102, v32
	v_max_f32_e32 v102, v81, v81
	v_max_f32_e32 v103, v80, v80
	v_max_f32_e32 v102, v103, v102
	v_max_f32_e32 v103, v85, v85
	v_max_f32_e32 v104, v84, v84
	v_max_f32_e32 v103, v104, v103
	v_max3_f32 v103, v82, v83, v103
	v_max3_f32 v32, v32, v102, v103
	ds_swizzle_b32 v102, v32 offset:swizzle(SWAP,16)
	v_mov_b32_e32 v103, v33
	v_mov_b32_e32 v133, v101
	s_waitcnt lgkmcnt(0)
	v_max_f32_e32 v102, v102, v102
	v_max_f32_e32 v32, v32, v102
	ds_bpermute_b32 v102, v110, v32
	s_waitcnt lgkmcnt(0)
	v_max3_f32 v132, 0, v32, v102
	v_sub_f32_e32 v32, 0, v132
	v_exp_f32_e32 v32, v32
	v_add_f32_e32 v100, v100, v132
	v_sub_f32_e32 v186, 0, v100
	v_mov_b32_e32 v187, v186
	v_mov_b32_e32 v188, v186
	v_mov_b32_e32 v189, v186
	v_mul_f32_e32 v92, v92, v32
	v_pk_mul_f32 v[68:69], v[68:69], v[32:33] op_sel_hi:[1,0]
	v_pk_mul_f32 v[66:67], v[66:67], v[32:33] op_sel_hi:[1,0]
	v_pk_mul_f32 v[64:65], v[64:65], v[32:33] op_sel_hi:[1,0]
	v_pk_mul_f32 v[62:63], v[62:63], v[32:33] op_sel_hi:[1,0]
	v_pk_mul_f32 v[60:61], v[60:61], v[32:33] op_sel_hi:[1,0]
	v_pk_mul_f32 v[58:59], v[58:59], v[32:33] op_sel_hi:[1,0]
	v_pk_mul_f32 v[56:57], v[56:57], v[32:33] op_sel_hi:[1,0]
	v_pk_mul_f32 v[54:55], v[54:55], v[32:33] op_sel_hi:[1,0]
	v_sub_f32_e32 v32, v78, v132
	v_exp_f32_e32 v127, v32
	v_sub_f32_e32 v32, v82, v132
	v_exp_f32_e32 v128, v32
	v_sub_f32_e32 v32, v79, v132
	v_exp_f32_e32 v134, v32
	v_sub_f32_e32 v32, v83, v132
	v_exp_f32_e32 v102, v32
	v_sub_f32_e32 v32, v80, v132
	v_add_f32_e32 v135, v127, v128
	v_exp_f32_e32 v129, v32
	v_sub_f32_e32 v32, v84, v132
	v_pk_add_f32 v[78:79], v[134:135], v[102:103]
	v_exp_f32_e32 v131, v32
	v_sub_f32_e32 v32, v81, v132
	v_pk_add_f32 v[106:107], v[78:79], v[78:79] op_sel_hi:[0,1]
	v_exp_f32_e32 v104, v32
	v_sub_f32_e32 v32, v85, v132
	v_exp_f32_e32 v106, v32
	v_add_f32_e32 v105, v129, v131
	v_mov_b32_e32 v32, v134
	v_pk_add_f32 v[78:79], v[104:105], v[106:107]
	s_nop 0
	v_add_f32_e32 v103, v78, v79

; template <int NC, int KS>
; DEVI void qk_half(const unsigned char* Kl, int krow, const bf16x8 (&q)[NC][KS], f32x4 (&s)[NC][2], int idx, int quad) {
; #pragma unroll
;   for (int u = 0; u < 2; ++u) {
; #pragma unroll
;     for (int c = 0; c < NC; ++c) s[c][u] = (f32x4){0.f, 0.f, 0.f, 0.f};
; #pragma unroll
;     for (int ks = 0; ks < KS; ++ks) {
;       bf16x8 kf = *(const bf16x8*)(Kl + (u * 16 + idx) * krow + ks * 64 + quad * 16);
; #pragma unroll
;       for (int c = 0; c < NC; ++c) s[c][u] = mfma16(kf, q[c][ks], s[c][u]);
;     }
;   }
; }
; template <int NC>
; DEVI void pv_half(const unsigned char* Vl, int vrow, const bf16x8 (&pb)[NC], f32x4 (&o)[NC][4], int idx, int quad) {
; #pragma unroll
;   for (int dvt = 0; dvt < 4; ++dvt) {
;     const unsigned char* p = Vl + (dvt * 16 + idx) * vrow + quad * 8;
;     u32x2 lo = *(const u32x2*)p, hi = *(const u32x2*)(p + 32);
;     bf16x8 vf = as_bf8((u32x4){lo.x, lo.y, hi.x, hi.y});
; #pragma unroll
;     for (int c = 0; c < NC; ++c) o[c][dvt] = mfma16(vf, pb[c], o[c][dvt]);
;   }
; }
; DEVI bf16x8 pack_p(const f32x4& a, const f32x4& b) { return as_bf8((u32x4){pk2(a[0], a[1]), pk2(a[2], a[3]), pk2(b[0], b[1]), pk2(b[2], b[3])}); }
; template <int NC, int KS, class MaskF>
; DEVI void attn_tile(const unsigned char* Kl, int krow, const unsigned char* Vl, const bf16x8 (&q)[NC][KS], f32x4 (&o)[NC][4],
;                     float (&mr)[NC], float (&lr)[NC], int idx, int quad, int mask_mode, bool lane_ok, const MaskF& mf) {
; #pragma unroll
;   for (int hf = 0; hf < 2; ++hf) {
;     f32x4 s[NC][2];
;     qk_half<NC, KS>(Kl + hf * 32 * krow, krow, q, s, idx, quad);
;     bf16x8 pb[NC];
; #pragma unroll
;     for (int c = 0; c < NC; ++c) {
;       if (mask_mode == 2) {
; #pragma unroll
;         for (int u = 0; u < 2; ++u)
; #pragma unroll
;           for (int j = 0; j < 4; ++j) s[c][u][j] = mf(c, hf * 32 + u * 16 + quad * 4 + j) ? s[c][u][j] : -1e30f;
;       } else if (mask_mode == 1) {
; #pragma unroll
;         for (int u = 0; u < 2; ++u)
; #pragma unroll
;           for (int j = 0; j < 4; ++j) s[c][u][j] = lane_ok ? s[c][u][j] : -1e30f;
;       }
;       float ps = 0.f;
;       f32x4 p0, p1;
; #pragma unroll
;       for (int j = 0; j < 4; ++j) { p0[j] = fexp2(s[c][0][j] - mr[c]); p1[j] = fexp2(s[c][1][j] - mr[c]); ps += p0[j] + p1[j]; }
;       if (__builtin_amdgcn_ballot_w64(!(ps <= 2048.f)) != 0ull) {
.LBB0_1375:
	s_or_b64 exec, exec, s[12:13]
	v_exp_f32_e32 v104, v70
	v_exp_f32_e32 v105, v74
	v_exp_f32_e32 v32, v71
	v_exp_f32_e32 v82, v75
	v_add_f32_e32 v83, v105, v104
	v_exp_f32_e32 v102, v77
	v_pk_add_f32 v[84:85], v[82:83], v[32:33]
	v_pk_add_f32 v[84:85], v[84:85], v[84:85] op_sel_hi:[0,1]
	v_exp_f32_e32 v83, v72
	v_exp_f32_e32 v106, v76
	v_exp_f32_e32 v84, v73
	v_add_f32_e32 v92, v103, v92
	v_add_f32_e32 v103, v106, v83
	v_pk_add_f32 v[126:127], v[102:103], v[84:85]
	s_nop 0
	v_add_f32_e32 v107, v126, v127
	v_cmp_nge_f32_e32 vcc, s94, v107
	s_cbranch_vccz .LBB0_1377
	v_max_f32_e32 v32, v71, v71
	v_max_f32_e32 v82, v70, v70
	v_max_f32_e32 v32, v82, v32
	v_max_f32_e32 v82, v73, v73
	v_max_f32_e32 v83, v72, v72
	v_max_f32_e32 v82, v83, v82
	v_max_f32_e32 v83, v77, v77
	v_max_f32_e32 v84, v76, v76
	v_max_f32_e32 v83, v84, v83
	v_max3_f32 v83, v74, v75, v83
	v_max3_f32 v32, v32, v82, v83
	ds_swizzle_b32 v82, v32 offset:swizzle(SWAP,16)
	v_mov_b32_e32 v83, v33
	s_waitcnt lgkmcnt(0)
	v_max_f32_e32 v82, v82, v82
	v_max_f32_e32 v32, v32, v82
	ds_bpermute_b32 v82, v110, v32
	s_waitcnt lgkmcnt(0)
	v_max3_f32 v107, 0, v32, v82
	v_sub_f32_e32 v32, 0, v107
	v_exp_f32_e32 v32, v32
	v_add_f32_e32 v101, v101, v107
	v_sub_f32_e32 v190, 0, v101
	v_mov_b32_e32 v191, v190
	v_mov_b32_e32 v192, v190
	v_mov_b32_e32 v193, v190
	v_mul_f32_e32 v93, v93, v32
	v_pk_mul_f32 v[52:53], v[52:53], v[32:33] op_sel_hi:[1,0]
	v_pk_mul_f32 v[50:51], v[50:51], v[32:33] op_sel_hi:[1,0]
	v_pk_mul_f32 v[48:49], v[48:49], v[32:33] op_sel_hi:[1,0]
	v_pk_mul_f32 v[46:47], v[46:47], v[32:33] op_sel_hi:[1,0]
	v_pk_mul_f32 v[44:45], v[44:45], v[32:33] op_sel_hi:[1,0]
	v_pk_mul_f32 v[42:43], v[42:43], v[32:33] op_sel_hi:[1,0]
	v_pk_mul_f32 v[40:41], v[40:41], v[32:33] op_sel_hi:[1,0]
	v_pk_mul_f32 v[38:39], v[38:39], v[32:33] op_sel_hi:[1,0]
	v_sub_f32_e32 v32, v70, v107
	v_exp_f32_e32 v104, v32
	v_sub_f32_e32 v32, v74, v107
	v_exp_f32_e32 v105, v32
	v_sub_f32_e32 v32, v71, v107
	v_exp_f32_e32 v126, v32
	v_sub_f32_e32 v32, v75, v107
	v_exp_f32_e32 v82, v32
	v_add_f32_e32 v127, v104, v105
	v_sub_f32_e32 v32, v72, v107
	v_pk_add_f32 v[70:71], v[126:127], v[82:83]
	v_exp_f32_e32 v83, v32
	v_sub_f32_e32 v32, v76, v107
	v_exp_f32_e32 v106, v32
	v_sub_f32_e32 v32, v73, v107
	v_pk_add_f32 v[102:103], v[70:71], v[70:71] op_sel_hi:[0,1]
	v_exp_f32_e32 v84, v32
	v_sub_f32_e32 v32, v77, v107
	v_exp_f32_e32 v102, v32
	v_add_f32_e32 v85, v83, v106
	v_mov_b32_e32 v32, v126
	v_pk_add_f32 v[70:71], v[84:85], v[102:103]
	s_nop 0
	v_add_f32_e32 v107, v70, v71
.LBB0_1377:
	s_mul_i32 s12, s18, 0x2400
	v_cvt_pk_bf16_f32 v70, v104, v32
	v_add_u32_e32 v32, s12, v119
	v_add_u32_e32 v125, 0x6800, v32
	ds_read2_b64 v[74:77], v125 offset1:4
	v_add_u32_e32 v126, 0x7000, v32
	v_cvt_pk_bf16_f32 v71, v83, v84
	v_cvt_pk_bf16_f32 v72, v105, v82
	v_cvt_pk_bf16_f32 v73, v106, v102
	v_add_u32_e32 v127, 0x7800, v32
	v_add_u32_e32 v128, 0x8000, v32
	ds_read_b128 v[82:85], v123 offset:6784
	ds_read_b128 v[102:105], v123 offset:10048
	s_waitcnt lgkmcnt(2)
	v_mfma_f32_16x16x32_bf16 v[66:69], v[74:77], v[78:81], v[66:69]
	v_add_u32_e32 v131, 32, v124
	v_add_u32_e32 v129, 34, v124
	v_mfma_f32_16x16x32_bf16 v[50:53], v[74:77], v[70:73], v[50:53]
	ds_read2_b64 v[74:77], v126 offset0:32 offset1:36
	s_waitcnt lgkmcnt(0)
	v_mfma_f32_16x16x32_bf16 v[62:65], v[74:77], v[78:81], v[62:65]
	v_mfma_f32_16x16x32_bf16 v[46:49], v[74:77], v[70:73], v[46:49]
	ds_read2_b64 v[74:77], v127 offset0:64 offset1:68
	s_waitcnt lgkmcnt(0)
	v_mfma_f32_16x16x32_bf16 v[58:61], v[74:77], v[78:81], v[58:61]
	v_mfma_f32_16x16x32_bf16 v[42:45], v[74:77], v[70:73], v[42:45]
	ds_read2_b64 v[74:77], v128 offset0:96 offset1:100
	s_waitcnt lgkmcnt(0)
	v_mfma_f32_16x16x32_bf16 v[38:41], v[74:77], v[70:73], v[38:41]
	ds_read_b128 v[70:73], v123 offset:6656
	v_mfma_f32_16x16x32_bf16 v[54:57], v[74:77], v[78:81], v[54:57]
	ds_read_b128 v[78:81], v123 offset:6720
	s_waitcnt lgkmcnt(1)
	v_mfma_f32_16x16x32_bf16 v[74:77], v[70:73], v[0:3], v[186:189]
	v_mfma_f32_16x16x32_bf16 v[70:73], v[70:73], v[12:15], v[190:193]
	s_waitcnt lgkmcnt(0)
	v_mfma_f32_16x16x32_bf16 v[74:77], v[78:81], v[4:7], v[74:77]
	v_mfma_f32_16x16x32_bf16 v[70:73], v[78:81], v[16:19], v[70:73]
	v_mfma_f32_16x16x32_bf16 v[78:81], v[82:85], v[8:11], v[74:77]
	s_nop 5
	ds_read_b128 v[74:77], v123 offset:9984
	v_mfma_f32_16x16x32_bf16 v[70:73], v[82:85], v[20:23], v[70:73]
	s_waitcnt lgkmcnt(0)
	v_mfma_f32_16x16x32_bf16 v[82:85], v[74:77], v[0:3], v[186:189]
	v_mfma_f32_16x16x32_bf16 v[74:77], v[74:77], v[12:15], v[190:193]
	v_mfma_f32_16x16x32_bf16 v[82:85], v[102:105], v[4:7], v[82:85]
	v_mfma_f32_16x16x32_bf16 v[74:77], v[102:105], v[16:19], v[74:77]
	ds_read_b128 v[102:105], v123 offset:10112
	v_add_u32_e32 v123, 35, v124
	s_waitcnt lgkmcnt(0)
	v_mfma_f32_16x16x32_bf16 v[82:85], v[102:105], v[8:11], v[82:85]
	v_mfma_f32_16x16x32_bf16 v[74:77], v[102:105], v[20:23], v[74:77]
	s_and_saveexec_b64 s[12:13], s[4:5]
	s_cbranch_execz .LBB0_1379
	v_cmp_le_i32_e32 vcc, v131, v109
	v_add_u32_e32 v32, 48, v124
	s_nop 0
	v_cndmask_b32_e32 v78, v238, v78, vcc
	v_cmp_lt_i32_e32 vcc, v131, v109
	s_nop 1
	v_cndmask_b32_e32 v79, v238, v79, vcc
	v_cmp_le_i32_e32 vcc, v129, v109
	s_nop 1
	v_cndmask_b32_e32 v80, v238, v80, vcc
	v_cmp_le_i32_e32 vcc, v123, v109
	s_nop 1
	v_cndmask_b32_e32 v81, v238, v81, vcc
	v_cmp_le_i32_e32 vcc, v32, v109
	v_add_u32_e32 v32, 49, v124
	s_nop 0
	v_cndmask_b32_e32 v82, v238, v82, vcc
	v_cmp_le_i32_e32 vcc, v32, v109
	v_add_u32_e32 v32, 50, v124
	s_nop 0
	v_cndmask_b32_e32 v83, v238, v83, vcc
	v_cmp_le_i32_e32 vcc, v32, v109
	v_add_u32_e32 v32, 51, v124
	s_nop 0
	v_cndmask_b32_e32 v84, v238, v84, vcc
	v_cmp_le_i32_e32 vcc, v32, v109
	s_nop 1
	v_cndmask_b32_e32 v85, v238, v85, vcc
; DEVI float fexp2(float x) { return __builtin_amdgcn_exp2f(x); }
; template <int M> DEVI float shx(float v) { return __int_as_float(__builtin_amdgcn_ds_swizzle(__float_as_int(v), (M << 10) | 0x1f)); }
; DEVI float shx32(float v, int lane) { return __int_as_float(__builtin_amdgcn_ds_bpermute((lane ^ 32) << 2, __float_as_int(v))); }
; template <int NC, int KS, class MaskF>
; DEVI void attn_tile(const unsigned char* Kl, int krow, const unsigned char* Vl, const bf16x8 (&q)[NC][KS], f32x4 (&o)[NC][4],
;                     float (&mr)[NC], float (&lr)[NC], int idx, int quad, int mask_mode, bool lane_ok, const MaskF& mf) {
;     ...
;       float ps = 0.f;
;       f32x4 p0, p1;
; #pragma unroll
;       for (int j = 0; j < 4; ++j) { p0[j] = fexp2(s[c][0][j] - mr[c]); p1[j] = fexp2(s[c][1][j] - mr[c]); ps += p0[j] + p1[j]; }
;       if (__builtin_amdgcn_ballot_w64(!(ps <= 2048.f)) != 0ull) {
;         float mx = fmaxf(fmaxf(fmaxf(s[c][0][0], s[c][0][1]), fmaxf(s[c][0][2], s[c][0][3])), fmaxf(fmaxf(s[c][1][0], s[c][1][1]), fmaxf(s[c][1][2], s[c][1][3])));
;         mx = fmaxf(mx, shx<16>(mx)); mx = fmaxf(mx, shx32(mx, quad * 16 + idx));
;         const float mnew = fmaxf(mr[c], mx);
;         const float alpha = fexp2(mr[c] - mnew);
;         lr[c] *= alpha; mr[c] = mnew;
; #pragma unroll
;         for (int dvt = 0; dvt < 4; ++dvt) o[c][dvt] *= alpha;
;         ps = 0.f;
; #pragma unroll
;         for (int j = 0; j < 4; ++j) { p0[j] = fexp2(s[c][0][j] - mnew); p1[j] = fexp2(s[c][1][j] - mnew); ps += p0[j] + p1[j]; }
;       }
;       lr[c] += ps;
;       s[c][0] = p0; s[c][1] = p1;
.LBB0_1379:
	s_or_b64 exec, exec, s[12:13]
	v_exp_f32_e32 v124, v78
	s_nop 1
	s_nop 0
	v_exp_f32_e32 v136, v82
	v_exp_f32_e32 v32, v79
	v_exp_f32_e32 v102, v83
	v_add_f32_e32 v103, v136, v124
	v_add_f32_e32 v93, v107, v93
	v_pk_add_f32 v[104:105], v[102:103], v[32:33]
	v_exp_f32_e32 v137, v80
	v_pk_add_f32 v[104:105], v[104:105], v[104:105] op_sel_hi:[0,1]
	v_exp_f32_e32 v138, v84
	v_exp_f32_e32 v104, v81
	v_exp_f32_e32 v106, v85
	v_add_f32_e32 v107, v138, v137
	v_pk_add_f32 v[132:133], v[106:107], v[104:105]
	s_nop 0
	v_add_f32_e32 v103, v132, v133
	v_cmp_nge_f32_e32 vcc, s94, v103
	s_cbranch_vccz .LBB0_1381
	v_max_f32_e32 v32, v79, v79
	v_max_f32_e32 v102, v78, v78
	v_max_f32_e32 v32, v102, v32
	v_max_f32_e32 v102, v81, v81
	v_max_f32_e32 v103, v80, v80
	v_max_f32_e32 v102, v103, v102
	v_max_f32_e32 v103, v85, v85
	v_max_f32_e32 v104, v84, v84
	v_max_f32_e32 v103, v104, v103
	v_max3_f32 v103, v82, v83, v103
	v_max3_f32 v32, v32, v102, v103
	ds_swizzle_b32 v102, v32 offset:swizzle(SWAP,16)
	v_mov_b32_e32 v103, v33
	v_mov_b32_e32 v133, v101
	s_waitcnt lgkmcnt(0)
	v_max_f32_e32 v102, v102, v102
	v_max_f32_e32 v32, v32, v102
	ds_bpermute_b32 v102, v110, v32
	s_waitcnt lgkmcnt(0)
	v_max3_f32 v132, 0, v32, v102
	v_sub_f32_e32 v32, 0, v132
	v_exp_f32_e32 v32, v32
	v_add_f32_e32 v100, v100, v132
	v_sub_f32_e32 v186, 0, v100
	v_mov_b32_e32 v187, v186
	v_mov_b32_e32 v188, v186
	v_mov_b32_e32 v189, v186
	v_mul_f32_e32 v92, v92, v32
	v_pk_mul_f32 v[68:69], v[68:69], v[32:33] op_sel_hi:[1,0]
	v_pk_mul_f32 v[66:67], v[66:67], v[32:33] op_sel_hi:[1,0]
	v_pk_mul_f32 v[64:65], v[64:65], v[32:33] op_sel_hi:[1,0]
	v_pk_mul_f32 v[62:63], v[62:63], v[32:33] op_sel_hi:[1,0]
	v_pk_mul_f32 v[60:61], v[60:61], v[32:33] op_sel_hi:[1,0]
	v_pk_mul_f32 v[58:59], v[58:59], v[32:33] op_sel_hi:[1,0]
	v_pk_mul_f32 v[56:57], v[56:57], v[32:33] op_sel_hi:[1,0]
	v_pk_mul_f32 v[54:55], v[54:55], v[32:33] op_sel_hi:[1,0]
	v_sub_f32_e32 v32, v78, v132
	v_exp_f32_e32 v124, v32
	v_sub_f32_e32 v32, v82, v132
	v_exp_f32_e32 v136, v32
	v_sub_f32_e32 v32, v79, v132
	v_exp_f32_e32 v134, v32
	v_sub_f32_e32 v32, v83, v132
	v_exp_f32_e32 v102, v32
	v_sub_f32_e32 v32, v80, v132
	v_add_f32_e32 v135, v124, v136
	v_exp_f32_e32 v137, v32
	v_sub_f32_e32 v32, v84, v132
	v_pk_add_f32 v[78:79], v[134:135], v[102:103]
	v_exp_f32_e32 v138, v32
	v_sub_f32_e32 v32, v81, v132
	v_pk_add_f32 v[106:107], v[78:79], v[78:79] op_sel_hi:[0,1]
	v_exp_f32_e32 v104, v32
	v_sub_f32_e32 v32, v85, v132
	v_exp_f32_e32 v106, v32
	v_add_f32_e32 v105, v137, v138
	v_mov_b32_e32 v32, v134
	v_pk_add_f32 v[78:79], v[104:105], v[106:107]
	s_nop 0
	v_add_f32_e32 v103, v78, v79

; DEVI float fexp2(float x) { return __builtin_amdgcn_exp2f(x); }
; template <int M> DEVI float shx(float v) { return __int_as_float(__builtin_amdgcn_ds_swizzle(__float_as_int(v), (M << 10) | 0x1f)); }
; DEVI float shx32(float v, int lane) { return __int_as_float(__builtin_amdgcn_ds_bpermute((lane ^ 32) << 2, __float_as_int(v))); }
; template <int NC, int KS, class MaskF>
; DEVI void attn_tile(const unsigned char* Kl, int krow, const unsigned char* Vl, const bf16x8 (&q)[NC][KS], f32x4 (&o)[NC][4],
;                     float (&mr)[NC], float (&lr)[NC], int idx, int quad, int mask_mode, bool lane_ok, const MaskF& mf) {
;     ...
;       float ps = 0.f;
;       f32x4 p0, p1;
; #pragma unroll
;       for (int j = 0; j < 4; ++j) { p0[j] = fexp2(s[c][0][j] - mr[c]); p1[j] = fexp2(s[c][1][j] - mr[c]); ps += p0[j] + p1[j]; }
;       if (__builtin_amdgcn_ballot_w64(!(ps <= 2048.f)) != 0ull) {
;         float mx = fmaxf(fmaxf(fmaxf(s[c][0][0], s[c][0][1]), fmaxf(s[c][0][2], s[c][0][3])), fmaxf(fmaxf(s[c][1][0], s[c][1][1]), fmaxf(s[c][1][2], s[c][1][3])));
;         mx = fmaxf(mx, shx<16>(mx)); mx = fmaxf(mx, shx32(mx, quad * 16 + idx));
;         const float mnew = fmaxf(mr[c], mx);
;         const float alpha = fexp2(mr[c] - mnew);
;         lr[c] *= alpha; mr[c] = mnew;
; #pragma unroll
;         for (int dvt = 0; dvt < 4; ++dvt) o[c][dvt] *= alpha;
;         ps = 0.f;
; #pragma unroll
;         for (int j = 0; j < 4; ++j) { p0[j] = fexp2(s[c][0][j] - mnew); p1[j] = fexp2(s[c][1][j] - mnew); ps += p0[j] + p1[j]; }
;       }
;       lr[c] += ps;
;       s[c][0] = p0; s[c][1] = p1;
.LBB0_1383:
	s_or_b64 exec, exec, s[12:13]
	v_exp_f32_e32 v104, v70
	v_exp_f32_e32 v105, v74
	v_exp_f32_e32 v32, v71
	v_exp_f32_e32 v82, v75
	v_add_f32_e32 v83, v105, v104
	v_exp_f32_e32 v102, v77
	v_pk_add_f32 v[84:85], v[82:83], v[32:33]
	v_pk_add_f32 v[84:85], v[84:85], v[84:85] op_sel_hi:[0,1]
	v_exp_f32_e32 v83, v72
	v_exp_f32_e32 v106, v76
	v_exp_f32_e32 v84, v73
	v_add_f32_e32 v92, v103, v92
	v_add_f32_e32 v103, v106, v83
	v_pk_add_f32 v[132:133], v[102:103], v[84:85]
	s_nop 0
	v_add_f32_e32 v85, v132, v133
	v_cmp_nge_f32_e32 vcc, s94, v85
	s_cbranch_vccz .LBB0_1385
	v_max_f32_e32 v32, v71, v71
	v_max_f32_e32 v82, v70, v70
	v_max_f32_e32 v32, v82, v32
	v_max_f32_e32 v82, v73, v73
	v_max_f32_e32 v83, v72, v72
	v_max_f32_e32 v82, v83, v82
	v_max_f32_e32 v83, v77, v77
	v_max_f32_e32 v84, v76, v76
	v_max_f32_e32 v83, v84, v83
	v_max3_f32 v83, v74, v75, v83
	v_max3_f32 v32, v32, v82, v83
	ds_swizzle_b32 v82, v32 offset:swizzle(SWAP,16)
	v_mov_b32_e32 v83, v33
	s_waitcnt lgkmcnt(0)
	v_max_f32_e32 v82, v82, v82
	v_max_f32_e32 v32, v32, v82
	ds_bpermute_b32 v82, v110, v32
	s_waitcnt lgkmcnt(0)
	v_max3_f32 v107, 0, v32, v82
	v_sub_f32_e32 v32, 0, v107
	v_exp_f32_e32 v32, v32
	v_add_f32_e32 v101, v101, v107
	v_sub_f32_e32 v190, 0, v101
	v_mov_b32_e32 v191, v190
	v_mov_b32_e32 v192, v190
	v_mov_b32_e32 v193, v190
	v_mul_f32_e32 v93, v93, v32
	v_pk_mul_f32 v[52:53], v[52:53], v[32:33] op_sel_hi:[1,0]
	v_pk_mul_f32 v[50:51], v[50:51], v[32:33] op_sel_hi:[1,0]
	v_pk_mul_f32 v[48:49], v[48:49], v[32:33] op_sel_hi:[1,0]
	v_pk_mul_f32 v[46:47], v[46:47], v[32:33] op_sel_hi:[1,0]
	v_pk_mul_f32 v[44:45], v[44:45], v[32:33] op_sel_hi:[1,0]
	v_pk_mul_f32 v[42:43], v[42:43], v[32:33] op_sel_hi:[1,0]
	v_pk_mul_f32 v[40:41], v[40:41], v[32:33] op_sel_hi:[1,0]
	v_pk_mul_f32 v[38:39], v[38:39], v[32:33] op_sel_hi:[1,0]
	v_sub_f32_e32 v32, v70, v107
	v_exp_f32_e32 v104, v32
	v_sub_f32_e32 v32, v74, v107
	v_exp_f32_e32 v105, v32
	v_sub_f32_e32 v32, v71, v107
	v_exp_f32_e32 v132, v32
	v_sub_f32_e32 v32, v75, v107
	v_exp_f32_e32 v82, v32
	v_add_f32_e32 v133, v104, v105
	v_sub_f32_e32 v32, v72, v107
	v_pk_add_f32 v[70:71], v[132:133], v[82:83]
	v_exp_f32_e32 v83, v32
	v_sub_f32_e32 v32, v76, v107
	v_exp_f32_e32 v106, v32
	v_sub_f32_e32 v32, v73, v107
	v_pk_add_f32 v[102:103], v[70:71], v[70:71] op_sel_hi:[0,1]
	v_exp_f32_e32 v84, v32
	v_sub_f32_e32 v32, v77, v107
	v_exp_f32_e32 v102, v32
	v_add_f32_e32 v85, v83, v106
	v_mov_b32_e32 v32, v132
	v_pk_add_f32 v[70:71], v[84:85], v[102:103]
	s_nop 0
	v_add_f32_e32 v85, v70, v71
